# v13 + gates skinny-GEMM items assigned only to the upper half of the grid (those workgroups have one w_in tile fewer)
# speedup vs baseline: 1.0005x; 1.0005x over previous
; __device__ __forceinline__ f32x4 mfma16(bf16x8 a, bf16x8 b, f32x4 c) { return __builtin_amdgcn_mfma_f32_16x16x32_bf16(a, b, c, 0, 0, 0); }
; __device__ __forceinline__ void gates_phase(const Args& a) {
;     const int tid = threadIdx.x, lane = tid & 63, wave = __builtin_amdgcn_readfirstlane(tid >> 6), g = lane >> 4, c16 = lane & 15;
;     const int gw = blockIdx.x * 8 + wave, NGW = gridDim.x * 8;
;     const bf16_t* XB = (const bf16_t*)(a.ws + WS_XB); const bf16_t* WG = (const bf16_t*)(a.ws + WS_WG);
;     const float* PS1 = (const float*)(a.ws + WS_PS1); float* GATES = (float*)(a.ws + WS_GATES);
;     const float bias = a.in[8][c16]; const bool isf = (c16 >> 2) & 1;
;     for (int it = gw; it < T / 16; it += NGW) {
;         const int r0 = it * 16; f32x4 acc = {0.f, 0.f, 0.f, 0.f};
;         const bf16_t* ap = XB + (size_t)(r0 + c16) * D + 8 * g; const bf16_t* bp = WG + (size_t)c16 * D + 8 * g;
; #pragma unroll 8
;         for (int kk = 0; kk < 32; ++kk) { const bf16x8 av = *(const bf16x8*)(ap + 32 * kk); const bf16x8 bv = *(const bf16x8*)(bp + 32 * kk); acc = mfma16(av, bv, acc); }
.LBB0_438:
	v_readfirstlane_b32 s0, v194
	s_lshr_b32 s4, s0, 6
	s_lshr_b32 s98, s58, 1
	s_cmp_lt_u32 s2, s98
	s_cbranch_scc1 .LBB0_451
	s_sub_i32 s99, s2, s98
	s_sub_i32 s100, s58, s98
	s_lshl_b32 s0, s99, 3
	s_add_i32 s3, s4, s0
	s_cmpk_gt_i32 s3, 0x17ff
	s_cbranch_scc1 .LBB0_451
	v_readlane_b32 s68, v253, 1
	s_waitcnt lgkmcnt(0)
	v_lshlrev_b64 v[2:3], 2, v[196:197]
	v_readlane_b32 s69, v253, 2
	v_bfe_u32 v8, v194, 4, 2
	v_lshlrev_b32_e32 v22, 2, v8
	v_lshl_add_u64 v[4:5], s[68:69], 0, v[2:3]
	global_load_dword v1, v[4:5], off
	v_and_b32_e32 v4, 4, v194
	v_cmp_ne_u32_e64 s[0:1], 0, v4
	v_lshlrev_b64 v[4:5], 11, v[196:197]
	v_lshlrev_b32_e32 v8, 4, v8
	s_lshl_b32 s5, s99, 7
	s_lshl_b32 s4, s4, 4
	v_lshl_add_u64 v[2:3], s[54:55], 0, v[2:3]
	s_mov_b64 s[8:9], 0x2f88000
	v_mov_b32_e32 v9, 0
	s_add_i32 s5, s5, s4
	v_or_b32_e32 v4, v4, v8
	s_lshl_b32 s6, s100, 3
	v_lshl_add_u64 v[6:7], v[2:3], 0, s[8:9]
	v_lshl_add_u64 v[10:11], s[54:55], 0, v[8:9]
	v_or_b32_e32 v12, s5, v196
	s_lshl_b32 s7, s100, 7
	v_lshl_add_u64 v[14:15], s[54:55], 0, v[4:5]
	v_mov_b32_e32 v8, 0x358637bd
	s_mov_b32 s8, 0x800000
	s_mov_b32 s9, 0xbfb8aa3b
	s_mov_b32 s10, 0x3f2aaaab
	v_mov_b32_e32 v23, 0x3ecc95a3
	s_mov_b32 s11, 0x3f317218
	s_mov_b32 s12, 0x7f800000
	s_mov_b32 s13, 0x33800000
	v_mov_b32_e32 v16, 0x3f317218
	v_mov_b32_e32 v24, 0x7f800000
	v_mov_b32_e32 v25, 0x7fc00000
	v_mov_b32_e32 v26, 0xff800000
	v_readlane_b32 s70, v253, 3
	v_readlane_b32 s71, v253, 4
	v_readlane_b32 s72, v253, 5
	v_readlane_b32 s73, v253, 6
	v_readlane_b32 s74, v253, 7
	v_readlane_b32 s75, v253, 8
	v_readlane_b32 s76, v253, 9
	v_readlane_b32 s77, v253, 10
	v_readlane_b32 s78, v253, 11
	v_readlane_b32 s79, v253, 12
	v_readlane_b32 s80, v253, 13
	v_readlane_b32 s81, v253, 14
	v_readlane_b32 s82, v253, 15
	v_readlane_b32 s83, v253, 16
	v_add_co_u32_e32 v64, vcc, 0x1a00000, v14
	s_nop 1
	v_addc_co_u32_e32 v65, vcc, 0, v15, vcc
	global_load_dwordx4 v[66:69], v[64:65], off
	global_load_dwordx4 v[70:73], v[64:65], off offset:64
	global_load_dwordx4 v[74:77], v[64:65], off offset:128
	global_load_dwordx4 v[78:81], v[64:65], off offset:192
	global_load_dwordx4 v[82:85], v[64:65], off offset:256
	global_load_dwordx4 v[86:89], v[64:65], off offset:320
	global_load_dwordx4 v[90:93], v[64:65], off offset:384
	global_load_dwordx4 v[94:97], v[64:65], off offset:448
	global_load_dwordx4 v[100:103], v[64:65], off offset:512
	global_load_dwordx4 v[104:107], v[64:65], off offset:576
	global_load_dwordx4 v[108:111], v[64:65], off offset:640
	global_load_dwordx4 v[112:115], v[64:65], off offset:704
	global_load_dwordx4 v[116:119], v[64:65], off offset:768
	global_load_dwordx4 v[120:123], v[64:65], off offset:832
	global_load_dwordx4 v[124:127], v[64:65], off offset:896
	global_load_dwordx4 v[142:145], v[64:65], off offset:960
	global_load_dwordx4 v[146:149], v[64:65], off offset:1024
	global_load_dwordx4 v[150:153], v[64:65], off offset:1088
	global_load_dwordx4 v[154:157], v[64:65], off offset:1152
	global_load_dwordx4 v[158:161], v[64:65], off offset:1216
	global_load_dwordx4 v[162:165], v[64:65], off offset:1280
	global_load_dwordx4 v[166:169], v[64:65], off offset:1344
	global_load_dwordx4 v[170:173], v[64:65], off offset:1408
	global_load_dwordx4 v[184:187], v[64:65], off offset:1472
	global_load_dwordx4 v[188:191], v[64:65], off offset:1536
	global_load_dwordx4 v[198:201], v[64:65], off offset:1600
	global_load_dwordx4 v[202:205], v[64:65], off offset:1664
	global_load_dwordx4 v[206:209], v[64:65], off offset:1728
	global_load_dwordx4 v[210:213], v[64:65], off offset:1792
	global_load_dwordx4 v[218:221], v[64:65], off offset:1856
	global_load_dwordx4 v[222:225], v[64:65], off offset:1920
	global_load_dwordx4 v[226:229], v[64:65], off offset:1984
	s_branch .LBB0_441
